# v9 + attention: known-result wave-uniform branch test after the bias chain replaced by a direct s_branch (both halves)
# speedup vs baseline: 1.0003x; 1.0003x over previous
; DI void attn_phase(LAS unsigned char* lds, ArgsRef a, int l, int vcu, int G) {
;     ...
;                 if (loc) {
;                     const int tb = (h * 15 + (kr - row) + 7) * 31 + 15 - qcol + 32 * cb + 8 * hg;
;                     const int kc0 = 32 * cb + 8 * hg;
; #pragma unroll
;                     for (int r = 0; r < 4; ++r)
; #pragma unroll
;                         for (int i = 0; i < 4; ++i) {
;                             const int kt = 16 * (r >> 1) + 4 * (r & 1) + i, kc = kc0 + kt;
;                             const bool valid = (kc >= cs) && (kc < cs + 16);
;                             const float bias = tab[valid ? tb + kt : 0];
;                             const float v = valid ? s[4 * r + i] * SC + bias : -1e30f;
;                             s[4 * r + i] = v; mx = fmaxf(mx, v);
;                         }
;                 } else {
; #pragma unroll
;                     for (int i = 0; i < 16; ++i) { const float v = s[i] * SC; s[i] = v; mx = fmaxf(mx, v); }
;                 }
;                 mx = fmaxf(mx, __shfl_xor(mx, 32));
.LattnA_done:
	s_mov_b64 s[6:7], 0
	s_branch .LBB0_388
